# seam barrier: non-leader workgroups poll the top-level generation word directly, per-XCD XGEN forwarding hop removed (one memory round trip less per seam)
# speedup vs baseline: 1.0064x; 1.0064x over previous
.LBB0_153:
	s_or_b64 exec, exec, s[12:13]
	v_cvt_f32_u32_e32 v5, v3
	s_waitcnt vmcnt(0)
	v_readfirstlane_b32 s3, v4
	v_sub_u32_e32 v4, 0, v3
	v_rcp_iflag_f32_e32 v5, v5
	v_add_u32_e32 v6, s3, v2
	v_mul_f32_e32 v5, 0x4f7ffffe, v5
	v_cvt_u32_f32_e32 v5, v5
	v_mul_lo_u32 v2, v4, v5
	v_mul_hi_u32 v2, v5, v2
	v_add_u32_e32 v2, v5, v2
	v_mul_hi_u32 v2, v6, v2
	v_mul_lo_u32 v4, v2, v3
	v_sub_u32_e32 v4, v6, v4
	v_add_u32_e32 v5, 1, v2
	v_cmp_ge_u32_e32 vcc, v4, v3
	s_nop 1
	v_cndmask_b32_e32 v2, v2, v5, vcc
	v_sub_u32_e32 v5, v4, v3
	v_cndmask_b32_e32 v4, v4, v5, vcc
	v_add_u32_e32 v5, 1, v2
	v_cmp_ge_u32_e32 vcc, v4, v3
	v_add_u32_e32 v4, 1, v6
	s_nop 0
	v_cndmask_b32_e32 v2, v2, v5, vcc
	v_mul_lo_u32 v5, v3, v2
	v_add_u32_e32 v3, v5, v3
	v_cmp_ne_u32_e32 vcc, v4, v3
	s_and_saveexec_b64 s[4:5], vcc
	s_xor_b64 s[12:13], exec, s[4:5]
	s_cbranch_execz .LBB0_184
	s_waitcnt lgkmcnt(0)
	s_add_u32 s18, s8, 0x83500
	s_addc_u32 s19, s9, 0
	v_mov_b32_e32 v1, 0
	global_load_dword v1, v1, s[18:19] sc1
	s_waitcnt vmcnt(0)
	v_cmp_eq_u32_e32 vcc, v1, v2
	s_and_saveexec_b64 s[14:15], vcc
	s_cbranch_execz .LBB0_183
	s_add_u32 s16, s8, 0x80200
	s_addc_u32 s17, s9, 0
	s_mov_b32 s3, 1
	s_mov_b64 s[20:21], 0
	v_mov_b32_e32 v1, 0
	s_branch .LBB0_157

.LBB0_218:
	s_or_b64 exec, exec, s[8:9]
	s_mov_b64 s[4:5], exec
	v_mbcnt_lo_u32_b32 v1, s4, 0
	v_mbcnt_hi_u32_b32 v1, s5, v1
	v_cmp_eq_u32_e32 vcc, 0, v1
	s_waitcnt vmcnt(0)
	buffer_inv sc1
	s_and_saveexec_b64 s[8:9], vcc
	s_cbranch_execz .LBB0_220
	s_bcnt1_i32_b64 s3, s[4:5]
	v_mov_b32_e32 v1, 0x2000
	v_mov_b32_e32 v2, s3
.LBB0_220:
	s_or_b64 exec, exec, s[8:9]
	s_waitcnt vmcnt(0)

.LBB0_295:
	s_or_b64 exec, exec, s[8:9]
	s_mov_b64 s[4:5], exec
	v_mbcnt_lo_u32_b32 v1, s4, 0
	v_mbcnt_hi_u32_b32 v1, s5, v1
	v_cmp_eq_u32_e32 vcc, 0, v1
	s_waitcnt vmcnt(0)
	buffer_inv sc1
	s_and_saveexec_b64 s[8:9], vcc
	s_cbranch_execz .LBB0_297
	s_bcnt1_i32_b64 s3, s[4:5]
	v_mov_b32_e32 v1, 0x2000
	v_mov_b32_e32 v2, s3
.LBB0_297:
	s_or_b64 exec, exec, s[8:9]
	s_waitcnt vmcnt(0)

.LBB0_516:
	s_or_b64 exec, exec, s[8:9]
	s_mov_b64 s[4:5], exec
	v_mbcnt_lo_u32_b32 v1, s4, 0
	v_mbcnt_hi_u32_b32 v1, s5, v1
	v_cmp_eq_u32_e32 vcc, 0, v1
	s_waitcnt vmcnt(0)
	buffer_inv sc1
	s_and_saveexec_b64 s[8:9], vcc
	s_cbranch_execz .LBB0_518
	s_bcnt1_i32_b64 s3, s[4:5]
	v_mov_b32_e32 v1, 0x2000
	v_mov_b32_e32 v2, s3
.LBB0_518:
	s_or_b64 exec, exec, s[8:9]
	s_waitcnt vmcnt(0)

.LBB0_616:
	s_or_b64 exec, exec, s[8:9]
	s_mov_b64 s[4:5], exec
	v_mbcnt_lo_u32_b32 v1, s4, 0
	v_mbcnt_hi_u32_b32 v1, s5, v1
	v_cmp_eq_u32_e32 vcc, 0, v1
	s_waitcnt vmcnt(0)
	buffer_inv sc1
	s_and_saveexec_b64 s[8:9], vcc
	s_cbranch_execz .LBB0_618
	s_bcnt1_i32_b64 s3, s[4:5]
	v_mov_b32_e32 v1, 0x2000
	v_mov_b32_e32 v2, s3
.LBB0_618:
	s_or_b64 exec, exec, s[8:9]
	s_waitcnt vmcnt(0)

.LBB0_754:
	s_or_b64 exec, exec, s[8:9]
	s_mov_b64 s[4:5], exec
	v_mbcnt_lo_u32_b32 v1, s4, 0
	v_mbcnt_hi_u32_b32 v1, s5, v1
	v_cmp_eq_u32_e32 vcc, 0, v1
	s_waitcnt vmcnt(0)
	buffer_inv sc1
	s_and_saveexec_b64 s[8:9], vcc
	s_cbranch_execz .LBB0_756
	s_bcnt1_i32_b64 s3, s[4:5]
	v_mov_b32_e32 v1, 0x2000
	v_mov_b32_e32 v2, s3
.LBB0_756:
	s_or_b64 exec, exec, s[8:9]
	s_waitcnt vmcnt(0)

.LBB0_829:
	s_or_b64 exec, exec, s[8:9]
	s_mov_b64 s[4:5], exec
	v_mbcnt_lo_u32_b32 v1, s4, 0
	v_mbcnt_hi_u32_b32 v1, s5, v1
	v_cmp_eq_u32_e32 vcc, 0, v1
	s_waitcnt vmcnt(0)
	buffer_inv sc1
	s_and_saveexec_b64 s[8:9], vcc
	s_cbranch_execz .LBB0_831
	s_bcnt1_i32_b64 s3, s[4:5]
	v_mov_b32_e32 v1, 0x2000
	v_mov_b32_e32 v2, s3
.LBB0_831:
	s_or_b64 exec, exec, s[8:9]
	s_waitcnt vmcnt(0)

.LBB0_920:
	s_or_b64 exec, exec, s[8:9]
	s_mov_b64 s[4:5], exec
	v_mbcnt_lo_u32_b32 v1, s4, 0
	v_mbcnt_hi_u32_b32 v1, s5, v1
	v_cmp_eq_u32_e32 vcc, 0, v1
	s_waitcnt vmcnt(0)
	buffer_inv sc1
	s_and_saveexec_b64 s[8:9], vcc
	s_cbranch_execz .LBB0_922
	s_bcnt1_i32_b64 s3, s[4:5]
	v_mov_b32_e32 v1, 0x2000
	v_mov_b32_e32 v2, s3
.LBB0_922:
	s_or_b64 exec, exec, s[8:9]
	s_waitcnt vmcnt(0)

.LBB0_998:
	s_or_b64 exec, exec, s[8:9]
	s_mov_b64 s[4:5], exec
	v_mbcnt_lo_u32_b32 v1, s4, 0
	v_mbcnt_hi_u32_b32 v1, s5, v1
	v_cmp_eq_u32_e32 vcc, 0, v1
	s_waitcnt vmcnt(0)
	buffer_inv sc1
	s_and_saveexec_b64 s[8:9], vcc
	s_cbranch_execz .LBB0_1000
	s_bcnt1_i32_b64 s3, s[4:5]
	v_mov_b32_e32 v1, 0x2000
	v_mov_b32_e32 v2, s3
.LBB0_1000:
	s_or_b64 exec, exec, s[8:9]
	s_waitcnt vmcnt(0)

.LBB0_1058:
	s_or_b64 exec, exec, s[6:7]
	v_cvt_f32_u32_e32 v5, v3
	s_waitcnt vmcnt(0)
	v_readfirstlane_b32 s4, v4
	v_sub_u32_e32 v4, 0, v3
	v_rcp_iflag_f32_e32 v5, v5
	v_add_u32_e32 v6, s4, v0
	v_mul_f32_e32 v5, 0x4f7ffffe, v5
	v_cvt_u32_f32_e32 v5, v5
	v_mul_lo_u32 v0, v4, v5
	v_mul_hi_u32 v0, v5, v0
	v_add_u32_e32 v0, v5, v0
	v_mul_hi_u32 v0, v6, v0
	v_mul_lo_u32 v4, v0, v3
	v_sub_u32_e32 v4, v6, v4
	v_add_u32_e32 v5, 1, v0
	v_cmp_ge_u32_e32 vcc, v4, v3
	s_nop 1
	v_cndmask_b32_e32 v0, v0, v5, vcc
	v_sub_u32_e32 v5, v4, v3
	v_cndmask_b32_e32 v4, v4, v5, vcc
	v_add_u32_e32 v5, 1, v0
	v_cmp_ge_u32_e32 vcc, v4, v3
	v_add_u32_e32 v4, 1, v6
	s_nop 0
	v_cndmask_b32_e32 v0, v0, v5, vcc
	v_mul_lo_u32 v5, v3, v0
	v_add_u32_e32 v3, v5, v3
	v_cmp_ne_u32_e32 vcc, v4, v3
	s_and_saveexec_b64 s[4:5], vcc
	s_xor_b64 s[14:15], exec, s[4:5]
	s_cbranch_execz .LBB0_1072
	s_waitcnt lgkmcnt(0)
	s_add_u32 s22, s10, 0x83500
	s_addc_u32 s23, s11, 0
	v_mov_b32_e32 v2, 0
	global_load_dword v2, v2, s[22:23] sc1
	s_waitcnt vmcnt(0)
	v_cmp_eq_u32_e32 vcc, v2, v0
	s_and_saveexec_b64 s[6:7], vcc
	s_cbranch_execz .LBB0_1071
	s_add_u32 s18, s10, 0x80200
	s_addc_u32 s19, s11, 0
	s_mov_b32 s28, 1
	s_mov_b64 s[26:27], 0
	s_branch .LBB0_1062

.LBB0_1089:
	s_or_b64 exec, exec, s[6:7]
	s_mov_b64 s[4:5], exec
	v_mbcnt_lo_u32_b32 v0, s4, 0
	v_mbcnt_hi_u32_b32 v0, s5, v0
	v_cmp_eq_u32_e32 vcc, 0, v0
	s_waitcnt vmcnt(0)
	buffer_inv sc1
	s_and_saveexec_b64 s[6:7], vcc
	s_cbranch_execz .LBB0_1091
	s_bcnt1_i32_b64 s4, s[4:5]
	v_mov_b32_e32 v0, s4
.LBB0_1091:
	s_or_b64 exec, exec, s[6:7]
	s_waitcnt vmcnt(0)

.LBB0_1164:
	s_or_b64 exec, exec, s[6:7]
	v_cvt_f32_u32_e32 v5, v3
	s_waitcnt vmcnt(0)
	v_readfirstlane_b32 s4, v4
	v_sub_u32_e32 v4, 0, v3
	v_rcp_iflag_f32_e32 v5, v5
	v_add_u32_e32 v6, s4, v0
	v_mul_f32_e32 v5, 0x4f7ffffe, v5
	v_cvt_u32_f32_e32 v5, v5
	v_mul_lo_u32 v0, v4, v5
	v_mul_hi_u32 v0, v5, v0
	v_add_u32_e32 v0, v5, v0
	v_mul_hi_u32 v0, v6, v0
	v_mul_lo_u32 v4, v0, v3
	v_sub_u32_e32 v4, v6, v4
	v_add_u32_e32 v5, 1, v0
	v_cmp_ge_u32_e32 vcc, v4, v3
	s_nop 1
	v_cndmask_b32_e32 v0, v0, v5, vcc
	v_sub_u32_e32 v5, v4, v3
	v_cndmask_b32_e32 v4, v4, v5, vcc
	v_add_u32_e32 v5, 1, v0
	v_cmp_ge_u32_e32 vcc, v4, v3
	v_add_u32_e32 v4, 1, v6
	s_nop 0
	v_cndmask_b32_e32 v0, v0, v5, vcc
	v_mul_lo_u32 v5, v3, v0
	v_add_u32_e32 v3, v5, v3
	v_cmp_ne_u32_e32 vcc, v4, v3
	s_and_saveexec_b64 s[4:5], vcc
	s_xor_b64 s[18:19], exec, s[4:5]
	s_cbranch_execz .LBB0_1195
	s_waitcnt lgkmcnt(0)
	s_add_u32 s26, s12, 0x83500
	s_addc_u32 s27, s13, 0
	v_mov_b32_e32 v2, 0
	global_load_dword v2, v2, s[26:27] sc1
	s_waitcnt vmcnt(0)
	v_cmp_eq_u32_e32 vcc, v2, v0
	s_and_saveexec_b64 s[6:7], vcc
	s_cbranch_execz .LBB0_1194
	s_add_u32 s22, s12, 0x80200
	s_addc_u32 s23, s13, 0
	s_mov_b32 s28, 1
	s_mov_b64 s[40:41], 0
	s_branch .LBB0_1168

.LBB0_1229:
	s_or_b64 exec, exec, s[6:7]
	s_mov_b64 s[4:5], exec
	v_mbcnt_lo_u32_b32 v0, s4, 0
	v_mbcnt_hi_u32_b32 v0, s5, v0
	v_cmp_eq_u32_e32 vcc, 0, v0
	s_waitcnt vmcnt(0)
	buffer_inv sc1
	s_and_saveexec_b64 s[6:7], vcc
	s_cbranch_execz .LBB0_1231
	s_bcnt1_i32_b64 s4, s[4:5]
	v_mov_b32_e32 v0, s4
.LBB0_1231:
	s_or_b64 exec, exec, s[6:7]
	s_waitcnt vmcnt(0)

.LBB0_1237:
	s_or_b64 exec, exec, s[6:7]
	s_mov_b64 s[4:5], exec
	v_mbcnt_lo_u32_b32 v0, s4, 0
	v_mbcnt_hi_u32_b32 v0, s5, v0
	v_cmp_eq_u32_e32 vcc, 0, v0
	s_waitcnt vmcnt(0)
	buffer_inv sc1
	s_and_saveexec_b64 s[6:7], vcc
	s_cbranch_execz .LBB0_1239
	s_bcnt1_i32_b64 s4, s[4:5]
	v_mov_b32_e32 v0, s4
.LBB0_1239:
	s_or_b64 exec, exec, s[6:7]
	s_waitcnt vmcnt(0)

.LBB0_1296:
	s_or_b64 exec, exec, s[6:7]
	v_cvt_f32_u32_e32 v5, v3
	s_waitcnt vmcnt(0)
	v_readfirstlane_b32 s4, v4
	v_sub_u32_e32 v4, 0, v3
	v_rcp_iflag_f32_e32 v5, v5
	v_add_u32_e32 v6, s4, v2
	v_mul_f32_e32 v5, 0x4f7ffffe, v5
	v_cvt_u32_f32_e32 v5, v5
	v_mul_lo_u32 v2, v4, v5
	v_mul_hi_u32 v2, v5, v2
	v_add_u32_e32 v2, v5, v2
	v_mul_hi_u32 v2, v6, v2
	v_mul_lo_u32 v4, v2, v3
	v_sub_u32_e32 v4, v6, v4
	v_add_u32_e32 v5, 1, v2
	v_cmp_ge_u32_e32 vcc, v4, v3
	s_nop 1
	v_cndmask_b32_e32 v2, v2, v5, vcc
	v_sub_u32_e32 v5, v4, v3
	v_cndmask_b32_e32 v4, v4, v5, vcc
	v_add_u32_e32 v5, 1, v2
	v_cmp_ge_u32_e32 vcc, v4, v3
	v_add_u32_e32 v4, 1, v6
	s_nop 0
	v_cndmask_b32_e32 v2, v2, v5, vcc
	v_mul_lo_u32 v5, v3, v2
	v_add_u32_e32 v3, v5, v3
	v_cmp_ne_u32_e32 vcc, v4, v3
	s_and_saveexec_b64 s[4:5], vcc
	s_xor_b64 s[14:15], exec, s[4:5]
	s_cbranch_execz .LBB0_1310
	s_waitcnt lgkmcnt(0)
	s_add_u32 s22, s10, 0x83500
	s_addc_u32 s23, s11, 0
	v_mov_b32_e32 v0, 0
	global_load_dword v0, v0, s[22:23] sc1
	s_waitcnt vmcnt(0)
	v_cmp_eq_u32_e32 vcc, v0, v2
	s_and_saveexec_b64 s[6:7], vcc
	s_cbranch_execz .LBB0_1309
	s_add_u32 s18, s10, 0x80200
	s_addc_u32 s19, s11, 0
	s_mov_b32 s21, 1
	s_mov_b64 s[26:27], 0
	s_branch .LBB0_1300

.LBB0_1327:
	s_or_b64 exec, exec, s[6:7]
	s_mov_b64 s[4:5], exec
	v_mbcnt_lo_u32_b32 v0, s4, 0
	v_mbcnt_hi_u32_b32 v0, s5, v0
	v_cmp_eq_u32_e32 vcc, 0, v0
	s_waitcnt vmcnt(0)
	buffer_inv sc1
	s_and_saveexec_b64 s[6:7], vcc
	s_cbranch_execz .LBB0_1329
	s_bcnt1_i32_b64 s4, s[4:5]
	v_mov_b32_e32 v0, s4
.LBB0_1329:
	s_or_b64 exec, exec, s[6:7]
	s_waitcnt vmcnt(0)

.LBB0_1406:
	s_or_b64 exec, exec, s[6:7]
	s_mov_b64 s[4:5], exec
	v_mbcnt_lo_u32_b32 v0, s4, 0
	v_mbcnt_hi_u32_b32 v0, s5, v0
	v_cmp_eq_u32_e32 vcc, 0, v0
	s_waitcnt vmcnt(0)
	buffer_inv sc1
	s_and_saveexec_b64 s[6:7], vcc
	s_cbranch_execz .LBB0_1408
	s_bcnt1_i32_b64 s4, s[4:5]
	v_mov_b32_e32 v0, s4
.LBB0_1408:
	s_or_b64 exec, exec, s[6:7]
	s_waitcnt vmcnt(0)

.LBB0_1482:
	s_or_b64 exec, exec, s[6:7]
	v_cvt_f32_u32_e32 v5, v3
	s_waitcnt vmcnt(0)
	v_readfirstlane_b32 s4, v4
	v_sub_u32_e32 v4, 0, v3
	v_rcp_iflag_f32_e32 v5, v5
	v_add_u32_e32 v6, s4, v2
	v_mul_f32_e32 v5, 0x4f7ffffe, v5
	v_cvt_u32_f32_e32 v5, v5
	v_mul_lo_u32 v2, v4, v5
	v_mul_hi_u32 v2, v5, v2
	v_add_u32_e32 v2, v5, v2
	v_mul_hi_u32 v2, v6, v2
	v_mul_lo_u32 v4, v2, v3
	v_sub_u32_e32 v4, v6, v4
	v_add_u32_e32 v5, 1, v2
	v_cmp_ge_u32_e32 vcc, v4, v3
	s_nop 1
	v_cndmask_b32_e32 v2, v2, v5, vcc
	v_sub_u32_e32 v5, v4, v3
	v_cndmask_b32_e32 v4, v4, v5, vcc
	v_add_u32_e32 v5, 1, v2
	v_cmp_ge_u32_e32 vcc, v4, v3
	v_add_u32_e32 v4, 1, v6
	s_nop 0
	v_cndmask_b32_e32 v2, v2, v5, vcc
	v_mul_lo_u32 v5, v3, v2
	v_add_u32_e32 v3, v5, v3
	v_cmp_ne_u32_e32 vcc, v4, v3
	s_and_saveexec_b64 s[4:5], vcc
	s_xor_b64 s[14:15], exec, s[4:5]
	s_cbranch_execz .LBB0_1496
	s_waitcnt lgkmcnt(0)
	s_add_u32 s22, s10, 0x83500
	s_addc_u32 s23, s11, 0
	v_mov_b32_e32 v0, 0
	global_load_dword v0, v0, s[22:23] sc1
	s_waitcnt vmcnt(0)
	v_cmp_eq_u32_e32 vcc, v0, v2
	s_and_saveexec_b64 s[6:7], vcc
	s_cbranch_execz .LBB0_1495
	s_add_u32 s18, s10, 0x80200
	s_addc_u32 s19, s11, 0
	s_mov_b32 s28, 1
	s_mov_b64 s[26:27], 0
	s_branch .LBB0_1486

.LBB0_1513:
	s_or_b64 exec, exec, s[6:7]
	s_mov_b64 s[4:5], exec
	v_mbcnt_lo_u32_b32 v0, s4, 0
	v_mbcnt_hi_u32_b32 v0, s5, v0
	v_cmp_eq_u32_e32 vcc, 0, v0
	s_waitcnt vmcnt(0)
	buffer_inv sc1
	s_and_saveexec_b64 s[6:7], vcc
	s_cbranch_execz .LBB0_1515
	s_bcnt1_i32_b64 s4, s[4:5]
	v_mov_b32_e32 v0, s4
.LBB0_1515:
	s_or_b64 exec, exec, s[6:7]
	s_waitcnt vmcnt(0)

.LBB0_1596:
	s_or_b64 exec, exec, s[6:7]
	s_mov_b64 s[4:5], exec
	v_mbcnt_lo_u32_b32 v0, s4, 0
	v_mbcnt_hi_u32_b32 v0, s5, v0
	v_cmp_eq_u32_e32 vcc, 0, v0
	s_waitcnt vmcnt(0)
	buffer_inv sc1
	s_and_saveexec_b64 s[6:7], vcc
	s_cbranch_execz .LBB0_1598
	s_bcnt1_i32_b64 s4, s[4:5]
	v_mov_b32_e32 v0, s4
.LBB0_1598:
	s_or_b64 exec, exec, s[6:7]
	s_waitcnt vmcnt(0)

.LBB0_1687:
	s_or_b64 exec, exec, s[6:7]
	s_mov_b64 s[4:5], exec
	v_mbcnt_lo_u32_b32 v0, s4, 0
	v_mbcnt_hi_u32_b32 v0, s5, v0
	v_cmp_eq_u32_e32 vcc, 0, v0
	s_waitcnt vmcnt(0)
	buffer_inv sc1
	s_and_saveexec_b64 s[6:7], vcc
	s_cbranch_execz .LBB0_1689
	s_bcnt1_i32_b64 s4, s[4:5]
	v_mov_b32_e32 v0, s4
.LBB0_1689:
	s_or_b64 exec, exec, s[6:7]
	s_waitcnt vmcnt(0)

.LBB0_1750:
	s_or_b64 exec, exec, s[6:7]
	v_cvt_f32_u32_e32 v5, v3
	s_waitcnt vmcnt(0)
	v_readfirstlane_b32 s4, v4
	v_sub_u32_e32 v4, 0, v3
	v_rcp_iflag_f32_e32 v5, v5
	v_add_u32_e32 v6, s4, v2
	v_mul_f32_e32 v5, 0x4f7ffffe, v5
	v_cvt_u32_f32_e32 v5, v5
	v_mul_lo_u32 v2, v4, v5
	v_mul_hi_u32 v2, v5, v2
	v_add_u32_e32 v2, v5, v2
	v_mul_hi_u32 v2, v6, v2
	v_mul_lo_u32 v4, v2, v3
	v_sub_u32_e32 v4, v6, v4
	v_add_u32_e32 v5, 1, v2
	v_cmp_ge_u32_e32 vcc, v4, v3
	s_nop 1
	v_cndmask_b32_e32 v2, v2, v5, vcc
	v_sub_u32_e32 v5, v4, v3
	v_cndmask_b32_e32 v4, v4, v5, vcc
	v_add_u32_e32 v5, 1, v2
	v_cmp_ge_u32_e32 vcc, v4, v3
	v_add_u32_e32 v4, 1, v6
	s_nop 0
	v_cndmask_b32_e32 v2, v2, v5, vcc
	v_mul_lo_u32 v5, v3, v2
	v_add_u32_e32 v3, v5, v3
	v_cmp_ne_u32_e32 vcc, v4, v3
	s_and_saveexec_b64 s[4:5], vcc
	s_xor_b64 s[18:19], exec, s[4:5]
	s_cbranch_execz .LBB0_1764
	s_waitcnt lgkmcnt(0)
	s_add_u32 s26, s12, 0x83500
	s_addc_u32 s27, s13, 0
	v_mov_b32_e32 v0, 0
	global_load_dword v0, v0, s[26:27] sc1
	s_waitcnt vmcnt(0)
	v_cmp_eq_u32_e32 vcc, v0, v2
	s_and_saveexec_b64 s[6:7], vcc
	s_cbranch_execz .LBB0_1763
	s_add_u32 s22, s12, 0x80200
	s_addc_u32 s23, s13, 0
	s_mov_b32 s21, 1
	s_mov_b64 s[40:41], 0
	s_branch .LBB0_1754

.LBB0_1781:
	s_or_b64 exec, exec, s[6:7]
	s_mov_b64 s[4:5], exec
	v_mbcnt_lo_u32_b32 v0, s4, 0
	v_mbcnt_hi_u32_b32 v0, s5, v0
	v_cmp_eq_u32_e32 vcc, 0, v0
	s_waitcnt vmcnt(0)
	buffer_inv sc1
	s_and_saveexec_b64 s[6:7], vcc
	s_cbranch_execz .LBB0_1003
	s_bcnt1_i32_b64 s4, s[4:5]
	v_mov_b32_e32 v0, s4
	s_branch .LBB0_1003

.LBB0_1788:
	s_or_b64 exec, exec, s[8:9]
	s_mov_b64 s[4:5], exec
	v_mbcnt_lo_u32_b32 v1, s4, 0
	v_mbcnt_hi_u32_b32 v1, s5, v1
	v_cmp_eq_u32_e32 vcc, 0, v1
	s_waitcnt vmcnt(0)
	buffer_inv sc1
	s_and_saveexec_b64 s[8:9], vcc
	s_cbranch_execz .LBB0_1790
	s_bcnt1_i32_b64 s3, s[4:5]
	v_mov_b32_e32 v1, 0x2000
	v_mov_b32_e32 v2, s3
.LBB0_1790:
	s_or_b64 exec, exec, s[8:9]
	s_waitcnt vmcnt(0)
